# v70: grid barrier spin loops keep two polls in flight (test the previous poll while the next is outstanding)
# speedup vs baseline: 1.0038x; 1.0014x over previous
.LBB0_111:
	s_or_b64 exec, exec, s[8:9]
	v_cvt_f32_u32_e32 v5, v3
	s_waitcnt vmcnt(0)
	v_readfirstlane_b32 s6, v4
	buffer_inv sc1
	v_sub_u32_e32 v4, 0, v3
	v_rcp_iflag_f32_e32 v5, v5
	v_add_u32_e32 v6, s6, v2
	v_mul_f32_e32 v5, 0x4f7ffffe, v5
	v_cvt_u32_f32_e32 v5, v5
	v_mul_lo_u32 v2, v4, v5
	v_mul_hi_u32 v2, v5, v2
	v_add_u32_e32 v2, v5, v2
	v_mul_hi_u32 v2, v6, v2
	v_mul_lo_u32 v4, v2, v3
	v_sub_u32_e32 v4, v6, v4
	v_add_u32_e32 v5, 1, v2
	v_cmp_ge_u32_e32 vcc, v4, v3
	s_nop 1
	v_cndmask_b32_e32 v2, v2, v5, vcc
	v_sub_u32_e32 v5, v4, v3
	v_cndmask_b32_e32 v4, v4, v5, vcc
	v_add_u32_e32 v5, 1, v2
	v_cmp_ge_u32_e32 vcc, v4, v3
	v_add_u32_e32 v4, 1, v6
	s_nop 0
	v_cndmask_b32_e32 v2, v2, v5, vcc
	v_mul_lo_u32 v5, v3, v2
	v_add_u32_e32 v3, v5, v3
	v_cmp_ne_u32_e32 vcc, v4, v3
	s_and_saveexec_b64 s[6:7], vcc
	s_xor_b64 s[6:7], exec, s[6:7]
	s_cbranch_execz .LBB0_125
	s_waitcnt lgkmcnt(0)
	v_mov_b32_e32 v1, 0x2000
	global_load_dword v1, v1, s[4:5] offset:1024 sc1
	s_add_u32 s12, s4, 0x2400
	s_addc_u32 s13, s5, 0
	s_waitcnt vmcnt(0)
	v_cmp_eq_u32_e32 vcc, v1, v2
	s_and_saveexec_b64 s[8:9], vcc
	s_cbranch_execz .LBB0_124
	s_add_u32 s10, s82, 0x4200
	s_addc_u32 s11, s83, 0
	s_mov_b32 s24, 1
	s_mov_b64 s[14:15], 0
	v_mov_b32_e32 v1, 0
	v_mov_b32_e32 v3, v2
	s_branch .LBB0_115

.LBB0_117:
	global_load_dword v3, v1, s[12:13] sc1
	s_add_i32 s24, s24, 1
	s_mov_b64 s[20:21], -1
	s_waitcnt vmcnt(1)
	v_cmp_ne_u32_e32 vcc, v3, v2
	s_orn2_b64 s[18:19], vcc, exec
	s_branch .LBB0_114
.LBB0_118:
	global_load_dword v253, v1, s[10:11] sc1
	s_waitcnt vmcnt(0)
	v_cmp_eq_u32_e32 vcc, 0, v253
	s_cbranch_vccnz .LBB0_120
	s_mov_b64 s[20:21], -1
	s_branch .LBB0_114

.LBB0_134:
	global_load_dword v2, v1, s[8:9] sc1
	s_add_i32 s24, s24, 1
	s_mov_b64 s[18:19], -1
	s_waitcnt vmcnt(1)
	v_cmp_ne_u32_e32 vcc, v2, v4
	s_orn2_b64 s[22:23], vcc, exec
	s_branch .LBB0_131
.LBB0_135:
	global_load_dword v253, v1, s[10:11] sc1
	s_waitcnt vmcnt(0)
	v_cmp_eq_u32_e32 vcc, 0, v253
	s_cbranch_vccnz .LBB0_137
	s_mov_b64 s[18:19], -1
	s_mov_b64 s[22:23], -1
	s_branch .LBB0_131

.LBB0_138:
	s_or_b64 exec, exec, s[14:15]
	s_waitcnt vmcnt(0)
	s_and_b64 s[14:15], s[16:17], exec

.LBB0_594:
	s_or_b64 exec, exec, s[6:7]
	v_cvt_f32_u32_e32 v5, v3
	s_waitcnt vmcnt(0)
	v_readfirstlane_b32 s4, v4
	buffer_inv sc1
	v_sub_u32_e32 v4, 0, v3
	v_rcp_iflag_f32_e32 v5, v5
	v_add_u32_e32 v6, s4, v2
	v_mul_f32_e32 v5, 0x4f7ffffe, v5
	v_cvt_u32_f32_e32 v5, v5
	v_mul_lo_u32 v2, v4, v5
	v_mul_hi_u32 v2, v5, v2
	v_add_u32_e32 v2, v5, v2
	v_mul_hi_u32 v2, v6, v2
	v_mul_lo_u32 v4, v2, v3
	v_sub_u32_e32 v4, v6, v4
	v_add_u32_e32 v5, 1, v2
	v_cmp_ge_u32_e32 vcc, v4, v3
	s_nop 1
	v_cndmask_b32_e32 v2, v2, v5, vcc
	v_sub_u32_e32 v5, v4, v3
	v_cndmask_b32_e32 v4, v4, v5, vcc
	v_add_u32_e32 v5, 1, v2
	v_cmp_ge_u32_e32 vcc, v4, v3
	v_add_u32_e32 v4, 1, v6
	s_nop 0
	v_cndmask_b32_e32 v2, v2, v5, vcc
	v_mul_lo_u32 v5, v3, v2
	v_add_u32_e32 v3, v5, v3
	v_cmp_ne_u32_e32 vcc, v4, v3
	s_and_saveexec_b64 s[4:5], vcc
	s_xor_b64 s[4:5], exec, s[4:5]
	s_cbranch_execz .LBB0_608
	s_waitcnt lgkmcnt(0)
	v_mov_b32_e32 v1, 0x2000
	global_load_dword v1, v1, s[2:3] offset:1024 sc1
	s_add_u32 s10, s2, 0x2400
	s_addc_u32 s11, s3, 0
	s_waitcnt vmcnt(0)
	v_cmp_eq_u32_e32 vcc, v1, v2
	s_and_saveexec_b64 s[6:7], vcc
	s_cbranch_execz .LBB0_607
	s_add_u32 s8, s82, 0x4200
	s_addc_u32 s9, s83, 0
	s_mov_b32 s24, 1
	s_mov_b64 s[12:13], 0
	v_mov_b32_e32 v1, 0
	v_mov_b32_e32 v3, v2
	s_branch .LBB0_598

.LBB0_600:
	global_load_dword v3, v1, s[10:11] sc1
	s_add_i32 s24, s24, 1
	s_mov_b64 s[20:21], -1
	s_waitcnt vmcnt(1)
	v_cmp_ne_u32_e32 vcc, v3, v2
	s_orn2_b64 s[18:19], vcc, exec
	s_branch .LBB0_597
.LBB0_601:
	global_load_dword v253, v1, s[8:9] sc1
	s_waitcnt vmcnt(0)
	v_cmp_eq_u32_e32 vcc, 0, v253
	s_cbranch_vccnz .LBB0_603
	s_mov_b64 s[20:21], -1
	s_branch .LBB0_597

.LBB0_617:
	global_load_dword v2, v1, s[6:7] sc1
	s_add_i32 s24, s24, 1
	s_mov_b64 s[18:19], -1
	s_waitcnt vmcnt(1)
	v_cmp_ne_u32_e32 vcc, v2, v4
	s_orn2_b64 s[22:23], vcc, exec
	s_branch .LBB0_614
.LBB0_618:
	global_load_dword v253, v1, s[8:9] sc1
	s_waitcnt vmcnt(0)
	v_cmp_eq_u32_e32 vcc, 0, v253
	s_cbranch_vccnz .LBB0_620
	s_mov_b64 s[18:19], -1
	s_mov_b64 s[22:23], -1
	s_branch .LBB0_614

.LBB0_621:
	s_or_b64 exec, exec, s[12:13]
	s_waitcnt vmcnt(0)
	s_and_b64 s[12:13], s[14:15], exec

.LBB0_1231:
	s_or_b64 exec, exec, s[6:7]
	v_cvt_f32_u32_e32 v5, v3
	s_waitcnt vmcnt(0)
	v_readfirstlane_b32 s4, v4
	buffer_inv sc1
	v_sub_u32_e32 v4, 0, v3
	v_rcp_iflag_f32_e32 v5, v5
	v_add_u32_e32 v6, s4, v2
	v_mul_f32_e32 v5, 0x4f7ffffe, v5
	v_cvt_u32_f32_e32 v5, v5
	v_mul_lo_u32 v2, v4, v5
	v_mul_hi_u32 v2, v5, v2
	v_add_u32_e32 v2, v5, v2
	v_mul_hi_u32 v2, v6, v2
	v_mul_lo_u32 v4, v2, v3
	v_sub_u32_e32 v4, v6, v4
	v_add_u32_e32 v5, 1, v2
	v_cmp_ge_u32_e32 vcc, v4, v3
	s_nop 1
	v_cndmask_b32_e32 v2, v2, v5, vcc
	v_sub_u32_e32 v5, v4, v3
	v_cndmask_b32_e32 v4, v4, v5, vcc
	v_add_u32_e32 v5, 1, v2
	v_cmp_ge_u32_e32 vcc, v4, v3
	v_add_u32_e32 v4, 1, v6
	s_nop 0
	v_cndmask_b32_e32 v2, v2, v5, vcc
	v_mul_lo_u32 v5, v3, v2
	v_add_u32_e32 v3, v5, v3
	v_cmp_ne_u32_e32 vcc, v4, v3
	s_and_saveexec_b64 s[4:5], vcc
	s_xor_b64 s[4:5], exec, s[4:5]
	s_cbranch_execz .LBB0_1245
	s_waitcnt lgkmcnt(0)
	v_mov_b32_e32 v1, 0x2000
	global_load_dword v1, v1, s[2:3] offset:1024 sc1
	s_add_u32 s10, s2, 0x2400
	s_addc_u32 s11, s3, 0
	s_waitcnt vmcnt(0)
	v_cmp_eq_u32_e32 vcc, v1, v2
	s_and_saveexec_b64 s[6:7], vcc
	s_cbranch_execz .LBB0_1244
	s_add_u32 s8, s82, 0x4200
	s_addc_u32 s9, s83, 0
	s_mov_b32 s22, 1
	s_mov_b64 s[12:13], 0
	v_mov_b32_e32 v1, 0
	v_mov_b32_e32 v3, v2
	s_branch .LBB0_1235

.LBB0_1237:
	global_load_dword v3, v1, s[10:11] sc1
	s_add_i32 s22, s22, 1
	s_mov_b64 s[18:19], -1
	s_waitcnt vmcnt(1)
	v_cmp_ne_u32_e32 vcc, v3, v2
	s_orn2_b64 s[16:17], vcc, exec
	s_branch .LBB0_1234
.LBB0_1238:
	global_load_dword v253, v1, s[8:9] sc1
	s_waitcnt vmcnt(0)
	v_cmp_eq_u32_e32 vcc, 0, v253
	s_cbranch_vccnz .LBB0_1240
	s_mov_b64 s[18:19], -1
	s_branch .LBB0_1234

.LBB0_1254:
	global_load_dword v2, v1, s[6:7] sc1
	s_add_i32 s22, s22, 1
	s_mov_b64 s[16:17], -1
	s_waitcnt vmcnt(1)
	v_cmp_ne_u32_e32 vcc, v2, v4
	s_orn2_b64 s[20:21], vcc, exec
	s_branch .LBB0_1251
.LBB0_1255:
	global_load_dword v253, v1, s[8:9] sc1
	s_waitcnt vmcnt(0)
	v_cmp_eq_u32_e32 vcc, 0, v253
	s_cbranch_vccnz .LBB0_1257
	s_mov_b64 s[16:17], -1
	s_mov_b64 s[20:21], -1
	s_branch .LBB0_1251

.LBB0_1571:
	s_or_b64 exec, exec, s[8:9]
	v_cvt_f32_u32_e32 v5, v3
	s_waitcnt vmcnt(0)
	v_readfirstlane_b32 s6, v4
	buffer_inv sc1
	v_sub_u32_e32 v4, 0, v3
	v_rcp_iflag_f32_e32 v5, v5
	v_add_u32_e32 v6, s6, v2
	v_mul_f32_e32 v5, 0x4f7ffffe, v5
	v_cvt_u32_f32_e32 v5, v5
	v_mul_lo_u32 v2, v4, v5
	v_mul_hi_u32 v2, v5, v2
	v_add_u32_e32 v2, v5, v2
	v_mul_hi_u32 v2, v6, v2
	v_mul_lo_u32 v4, v2, v3
	v_sub_u32_e32 v4, v6, v4
	v_add_u32_e32 v5, 1, v2
	v_cmp_ge_u32_e32 vcc, v4, v3
	s_nop 1
	v_cndmask_b32_e32 v2, v2, v5, vcc
	v_sub_u32_e32 v5, v4, v3
	v_cndmask_b32_e32 v4, v4, v5, vcc
	v_add_u32_e32 v5, 1, v2
	v_cmp_ge_u32_e32 vcc, v4, v3
	v_add_u32_e32 v4, 1, v6
	s_nop 0
	v_cndmask_b32_e32 v2, v2, v5, vcc
	v_mul_lo_u32 v5, v3, v2
	v_add_u32_e32 v3, v5, v3
	v_cmp_ne_u32_e32 vcc, v4, v3
	s_and_saveexec_b64 s[6:7], vcc
	s_xor_b64 s[6:7], exec, s[6:7]
	s_cbranch_execz .LBB0_1585
	s_waitcnt lgkmcnt(0)
	v_mov_b32_e32 v1, 0x2000
	global_load_dword v1, v1, s[2:3] offset:1024 sc1
	s_add_u32 s12, s2, 0x2400
	s_addc_u32 s13, s3, 0
	s_waitcnt vmcnt(0)
	v_cmp_eq_u32_e32 vcc, v1, v2
	s_and_saveexec_b64 s[8:9], vcc
	s_cbranch_execz .LBB0_1584
	s_add_u32 s10, s82, 0x4200
	s_addc_u32 s11, s83, 0
	s_mov_b32 s24, 1
	s_mov_b64 s[14:15], 0
	v_mov_b32_e32 v1, 0
	v_mov_b32_e32 v3, v2
	s_branch .LBB0_1575

.LBB0_1855:
	s_or_b64 exec, exec, s[6:7]
	v_cvt_f32_u32_e32 v5, v3
	s_waitcnt vmcnt(0)
	v_readfirstlane_b32 s4, v4
	buffer_inv sc1
	v_sub_u32_e32 v4, 0, v3
	v_rcp_iflag_f32_e32 v5, v5
	v_add_u32_e32 v6, s4, v2
	v_mul_f32_e32 v5, 0x4f7ffffe, v5
	v_cvt_u32_f32_e32 v5, v5
	v_mul_lo_u32 v2, v4, v5
	v_mul_hi_u32 v2, v5, v2
	v_add_u32_e32 v2, v5, v2
	v_mul_hi_u32 v2, v6, v2
	v_mul_lo_u32 v4, v2, v3
	v_sub_u32_e32 v4, v6, v4
	v_add_u32_e32 v5, 1, v2
	v_cmp_ge_u32_e32 vcc, v4, v3
	s_nop 1
	v_cndmask_b32_e32 v2, v2, v5, vcc
	v_sub_u32_e32 v5, v4, v3
	v_cndmask_b32_e32 v4, v4, v5, vcc
	v_add_u32_e32 v5, 1, v2
	v_cmp_ge_u32_e32 vcc, v4, v3
	v_add_u32_e32 v4, 1, v6
	s_nop 0
	v_cndmask_b32_e32 v2, v2, v5, vcc
	v_mul_lo_u32 v5, v3, v2
	v_add_u32_e32 v3, v5, v3
	v_cmp_ne_u32_e32 vcc, v4, v3
	s_and_saveexec_b64 s[4:5], vcc
	s_xor_b64 s[4:5], exec, s[4:5]
	s_cbranch_execz .LBB0_1869
	s_waitcnt lgkmcnt(0)
	v_mov_b32_e32 v1, 0x2000
	global_load_dword v1, v1, s[2:3] offset:1024 sc1
	s_add_u32 s12, s2, 0x2400
	s_addc_u32 s13, s3, 0
	s_waitcnt vmcnt(0)
	v_cmp_eq_u32_e32 vcc, v1, v2
	s_and_saveexec_b64 s[6:7], vcc
	s_cbranch_execz .LBB0_1868
	s_add_u32 s8, s82, 0x4200
	s_addc_u32 s9, s83, 0
	s_mov_b32 s24, 1
	s_mov_b64 s[14:15], 0
	v_mov_b32_e32 v1, 0
	v_mov_b32_e32 v3, v2
	s_branch .LBB0_1859
